# v5 + peeled first K iteration (C=0, no accumulator zeroing) + de-serialised residual epilogue loads + s_andn2 instead of cndmask/cmp in the diff-attention loops + address updates moved into the MFMA->
# speedup vs baseline: 1.0083x; 1.0009x over previous
.LBB0_582:
	s_andn2_b64 s[4:5], exec, s[6:7]
	s_andn2_b64 vcc, exec, s[6:7]
	s_cbranch_vccnz .LBB0_584
	s_sub_i32 s6, s51, 64
	s_and_b32 s6, s6, 0x1f80
	s_lshl_b32 s8, s6, 1
	v_lshl_add_u64 v[112:113], v[214:215], 0, s[8:9]
	v_add_co_u32_e32 v114, vcc, 0x100000, v112
	s_nop 1
	v_addc_co_u32_e32 v115, vcc, 0, v113, vcc
	global_load_dwordx4 v[196:199], v[112:113], off
	global_load_dwordx4 v[200:203], v[114:115], off
.LBB0_584:
	ds_read_b128 v[112:115], v213 offset:9216
	ds_read_b128 v[128:131], v213 offset:9248
	ds_read_b128 v[132:135], v213 offset:13824
	ds_read_b128 v[136:139], v213 offset:13856
	v_exp_f32_e32 v172, v92
	v_exp_f32_e32 v173, v93
	s_waitcnt lgkmcnt(3)
	v_mfma_f32_32x32x16_bf16 v[144:159], v[112:115], v[176:179], v[16:31]
	v_exp_f32_e32 v174, v94
	v_exp_f32_e32 v175, v95
	s_andn2_b64 vcc, exec, s[18:19]
	s_waitcnt lgkmcnt(2)
	v_mfma_f32_32x32x16_bf16 v[144:159], v[128:131], v[180:183], v[144:159]
	s_waitcnt lgkmcnt(1)
	v_mfma_f32_32x32x16_bf16 v[112:127], v[132:135], v[176:179], v[16:31]
	ds_read_b128 v[128:131], v213 offset:9280
	ds_read_b128 v[132:135], v213 offset:9312
	ds_read_b128 v[140:143], v213 offset:13888
	ds_read_b128 v[228:231], v213 offset:13920
	ds_read_b128 v[160:163], v208 offset:18464
	s_waitcnt lgkmcnt(4)
	v_mfma_f32_32x32x16_bf16 v[144:159], v[128:131], v[184:187], v[144:159]
	v_exp_f32_e32 v128, v96
	v_exp_f32_e32 v129, v97
	v_exp_f32_e32 v130, v98
	v_exp_f32_e32 v131, v99
	ds_read_b128 v[96:99], v208 offset:18432
	s_waitcnt lgkmcnt(4)
	v_mfma_f32_32x32x16_bf16 v[144:159], v[132:135], v[188:191], v[144:159]
	v_exp_f32_e32 v132, v100
	v_exp_f32_e32 v133, v101
	v_exp_f32_e32 v134, v102
	v_exp_f32_e32 v135, v103
	v_cvt_pk_bf16_f32 v100, v128, v129
	v_cvt_pk_bf16_f32 v101, v130, v131
	v_cvt_pk_bf16_f32 v102, v132, v133
	v_cvt_pk_bf16_f32 v103, v134, v135
	v_mfma_f32_32x32x16_bf16 v[112:127], v[136:139], v[180:183], v[112:127]
	v_exp_f32_e32 v136, v104
	v_exp_f32_e32 v137, v105
	v_exp_f32_e32 v138, v106
	v_exp_f32_e32 v139, v107
	s_waitcnt lgkmcnt(0)
	v_mfma_f32_32x32x16_bf16 v[64:79], v[96:99], v[100:103], v[64:79]
	ds_read_b128 v[96:99], v208 offset:23040
	ds_read_b128 v[164:167], v208 offset:23072
	s_waitcnt lgkmcnt(1)
	v_mfma_f32_32x32x16_bf16 v[48:63], v[96:99], v[100:103], v[48:63]
	ds_read_b128 v[96:99], v208 offset:27648
	ds_read_b128 v[168:171], v208 offset:27680
	ds_read_b128 v[104:107], v208 offset:32288
	s_waitcnt lgkmcnt(2)
	v_mfma_f32_32x32x16_bf16 v[32:47], v[96:99], v[100:103], v[32:47]
	ds_read_b128 v[96:99], v208 offset:32256
	v_mfma_f32_32x32x16_bf16 v[112:127], v[140:143], v[184:187], v[112:127]
	v_exp_f32_e32 v140, v108
	v_exp_f32_e32 v141, v109
	v_exp_f32_e32 v142, v110
	v_exp_f32_e32 v143, v111
	s_waitcnt lgkmcnt(0)
	v_mfma_f32_32x32x16_bf16 v[0:15], v[96:99], v[100:103], v[0:15]
	v_cvt_pk_bf16_f32 v96, v136, v137
	v_cvt_pk_bf16_f32 v97, v138, v139
	v_cvt_pk_bf16_f32 v98, v140, v141
	v_cvt_pk_bf16_f32 v99, v142, v143
	s_nop 1
	v_mfma_f32_32x32x16_bf16 v[64:79], v[160:163], v[96:99], v[64:79]
	v_exp_f32_e32 v160, v80
	v_exp_f32_e32 v161, v81
	v_exp_f32_e32 v162, v82
	v_exp_f32_e32 v163, v83
	ds_read_b128 v[80:83], v208 offset:18496
	v_mfma_f32_32x32x16_bf16 v[48:63], v[164:167], v[96:99], v[48:63]
	v_exp_f32_e32 v164, v84
	v_exp_f32_e32 v165, v85
	v_exp_f32_e32 v166, v86
	v_exp_f32_e32 v167, v87
	v_cvt_pk_bf16_f32 v84, v160, v161
	v_cvt_pk_bf16_f32 v85, v162, v163
	v_cvt_pk_bf16_f32 v86, v164, v165
	v_cvt_pk_bf16_f32 v87, v166, v167
	v_mfma_f32_32x32x16_bf16 v[32:47], v[168:171], v[96:99], v[32:47]
	v_exp_f32_e32 v168, v88
	v_exp_f32_e32 v169, v89
	v_exp_f32_e32 v170, v90
	v_exp_f32_e32 v171, v91
	v_mfma_f32_32x32x16_bf16 v[0:15], v[104:107], v[96:99], v[0:15]
	ds_read_b128 v[96:99], v208 offset:18528
	s_waitcnt lgkmcnt(1)
	v_mfma_f32_32x32x16_bf16 v[64:79], v[80:83], v[84:87], v[64:79]
	ds_read_b128 v[80:83], v208 offset:23104
	ds_read_b128 v[100:103], v208 offset:23136
	s_waitcnt lgkmcnt(1)
	v_mfma_f32_32x32x16_bf16 v[48:63], v[80:83], v[84:87], v[48:63]
	ds_read_b128 v[80:83], v208 offset:27712
	ds_read_b128 v[104:107], v208 offset:27744
	ds_read_b128 v[88:91], v208 offset:32352
	s_waitcnt lgkmcnt(2)
	v_mfma_f32_32x32x16_bf16 v[32:47], v[80:83], v[84:87], v[32:47]
	ds_read_b128 v[80:83], v208 offset:32320
	s_waitcnt lgkmcnt(0)
	s_barrier
	v_mfma_f32_32x32x16_bf16 v[0:15], v[80:83], v[84:87], v[0:15]
	v_cvt_pk_bf16_f32 v80, v168, v169
	v_cvt_pk_bf16_f32 v81, v170, v171
	v_cvt_pk_bf16_f32 v82, v172, v173
	v_cvt_pk_bf16_f32 v83, v174, v175
	s_nop 1
	v_mfma_f32_32x32x16_bf16 v[64:79], v[96:99], v[80:83], v[64:79]
	v_mfma_f32_32x32x16_bf16 v[48:63], v[100:103], v[80:83], v[48:63]
	v_mfma_f32_32x32x16_bf16 v[32:47], v[104:107], v[80:83], v[32:47]
	v_mfma_f32_32x32x16_bf16 v[0:15], v[88:91], v[80:83], v[0:15]
	s_andn2_b64 s[6:7], exec, s[18:19]
	v_mfma_f32_32x32x16_bf16 v[112:127], v[228:231], v[188:191], v[112:127]
	s_cbranch_vccnz .LBB0_589
	s_waitcnt vmcnt(0)
	ds_write_b128 v211, v[192:195] offset:9216
	s_and_b64 vcc, exec, s[4:5]
	s_cbranch_vccz .LBB0_590

.LBB0_601:
	s_andn2_b64 s[4:5], exec, s[6:7]
	s_andn2_b64 vcc, exec, s[6:7]
	s_cbranch_vccnz .LBB0_603
	s_sub_i32 s6, s19, 64
	s_and_b32 s6, s6, 0x1f80
	s_lshl_b32 s8, s6, 1
	v_lshl_add_u64 v[112:113], v[216:217], 0, s[8:9]
	v_add_co_u32_e32 v114, vcc, 0x100000, v112
	s_nop 1
	v_addc_co_u32_e32 v115, vcc, 0, v113, vcc
	global_load_dwordx4 v[196:199], v[112:113], off
	global_load_dwordx4 v[200:203], v[114:115], off
.LBB0_603:
	ds_read_b128 v[112:115], v225 offset:9216
	ds_read_b128 v[128:131], v225 offset:9248
	ds_read_b128 v[132:135], v225 offset:13824
	ds_read_b128 v[136:139], v225 offset:13856
	v_exp_f32_e32 v172, v92
	v_exp_f32_e32 v173, v93
	s_waitcnt lgkmcnt(3)
	v_mfma_f32_32x32x16_bf16 v[144:159], v[112:115], v[176:179], v[64:79]
	v_exp_f32_e32 v174, v94
	v_exp_f32_e32 v175, v95
	s_andn2_b64 vcc, exec, s[16:17]
	s_waitcnt lgkmcnt(2)
	v_mfma_f32_32x32x16_bf16 v[144:159], v[128:131], v[180:183], v[144:159]
	s_waitcnt lgkmcnt(1)
	v_mfma_f32_32x32x16_bf16 v[112:127], v[132:135], v[176:179], v[64:79]
	ds_read_b128 v[128:131], v225 offset:9280
	ds_read_b128 v[132:135], v225 offset:9312
	ds_read_b128 v[140:143], v225 offset:13888
	ds_read_b128 v[228:231], v225 offset:13920
	ds_read_b128 v[160:163], v208 offset:18464
	s_waitcnt lgkmcnt(4)
	v_mfma_f32_32x32x16_bf16 v[144:159], v[128:131], v[184:187], v[144:159]
	v_exp_f32_e32 v128, v96
	v_exp_f32_e32 v129, v97
	v_exp_f32_e32 v130, v98
	v_exp_f32_e32 v131, v99
	ds_read_b128 v[96:99], v208 offset:18432
	s_waitcnt lgkmcnt(4)
	v_mfma_f32_32x32x16_bf16 v[144:159], v[132:135], v[188:191], v[144:159]
	v_exp_f32_e32 v132, v100
	v_exp_f32_e32 v133, v101
	v_exp_f32_e32 v134, v102
	v_exp_f32_e32 v135, v103
	v_cvt_pk_bf16_f32 v100, v128, v129
	v_cvt_pk_bf16_f32 v101, v130, v131
	v_cvt_pk_bf16_f32 v102, v132, v133
	v_cvt_pk_bf16_f32 v103, v134, v135
	v_mfma_f32_32x32x16_bf16 v[112:127], v[136:139], v[180:183], v[112:127]
	v_exp_f32_e32 v136, v104
	v_exp_f32_e32 v137, v105
	v_exp_f32_e32 v138, v106
	v_exp_f32_e32 v139, v107
	s_waitcnt lgkmcnt(0)
	v_mfma_f32_32x32x16_bf16 v[0:15], v[96:99], v[100:103], v[0:15]
	ds_read_b128 v[96:99], v208 offset:23040
	ds_read_b128 v[164:167], v208 offset:23072
	s_waitcnt lgkmcnt(1)
	v_mfma_f32_32x32x16_bf16 v[48:63], v[96:99], v[100:103], v[48:63]
	ds_read_b128 v[96:99], v208 offset:27648
	ds_read_b128 v[168:171], v208 offset:27680
	ds_read_b128 v[104:107], v208 offset:32288
	s_waitcnt lgkmcnt(2)
	v_mfma_f32_32x32x16_bf16 v[32:47], v[96:99], v[100:103], v[32:47]
	ds_read_b128 v[96:99], v208 offset:32256
	v_mfma_f32_32x32x16_bf16 v[112:127], v[140:143], v[184:187], v[112:127]
	v_exp_f32_e32 v140, v108
	v_exp_f32_e32 v141, v109
	v_exp_f32_e32 v142, v110
	v_exp_f32_e32 v143, v111
	s_waitcnt lgkmcnt(0)
	v_mfma_f32_32x32x16_bf16 v[16:31], v[96:99], v[100:103], v[16:31]
	v_cvt_pk_bf16_f32 v96, v136, v137
	v_cvt_pk_bf16_f32 v97, v138, v139
	v_cvt_pk_bf16_f32 v98, v140, v141
	v_cvt_pk_bf16_f32 v99, v142, v143
	s_nop 1
	v_mfma_f32_32x32x16_bf16 v[0:15], v[160:163], v[96:99], v[0:15]
	v_exp_f32_e32 v160, v80
	v_exp_f32_e32 v161, v81
	v_exp_f32_e32 v162, v82
	v_exp_f32_e32 v163, v83
	ds_read_b128 v[80:83], v208 offset:18496
	v_mfma_f32_32x32x16_bf16 v[48:63], v[164:167], v[96:99], v[48:63]
	v_exp_f32_e32 v164, v84
	v_exp_f32_e32 v165, v85
	v_exp_f32_e32 v166, v86
	v_exp_f32_e32 v167, v87
	v_cvt_pk_bf16_f32 v84, v160, v161
	v_cvt_pk_bf16_f32 v85, v162, v163
	v_cvt_pk_bf16_f32 v86, v164, v165
	v_cvt_pk_bf16_f32 v87, v166, v167
	v_mfma_f32_32x32x16_bf16 v[32:47], v[168:171], v[96:99], v[32:47]
	v_exp_f32_e32 v168, v88
	v_exp_f32_e32 v169, v89
	v_exp_f32_e32 v170, v90
	v_exp_f32_e32 v171, v91
	v_mfma_f32_32x32x16_bf16 v[16:31], v[104:107], v[96:99], v[16:31]
	ds_read_b128 v[96:99], v208 offset:18528
	s_waitcnt lgkmcnt(1)
	v_mfma_f32_32x32x16_bf16 v[0:15], v[80:83], v[84:87], v[0:15]
	ds_read_b128 v[80:83], v208 offset:23104
	ds_read_b128 v[100:103], v208 offset:23136
	s_waitcnt lgkmcnt(1)
	v_mfma_f32_32x32x16_bf16 v[48:63], v[80:83], v[84:87], v[48:63]
	ds_read_b128 v[80:83], v208 offset:27712
	ds_read_b128 v[104:107], v208 offset:27744
	ds_read_b128 v[88:91], v208 offset:32352
	s_waitcnt lgkmcnt(2)
	v_mfma_f32_32x32x16_bf16 v[32:47], v[80:83], v[84:87], v[32:47]
	ds_read_b128 v[80:83], v208 offset:32320
	s_waitcnt lgkmcnt(0)
	s_barrier
	v_mfma_f32_32x32x16_bf16 v[16:31], v[80:83], v[84:87], v[16:31]
	v_cvt_pk_bf16_f32 v80, v168, v169
	v_cvt_pk_bf16_f32 v81, v170, v171
	v_cvt_pk_bf16_f32 v82, v172, v173
	v_cvt_pk_bf16_f32 v83, v174, v175
	s_nop 1
	v_mfma_f32_32x32x16_bf16 v[0:15], v[96:99], v[80:83], v[0:15]
	v_mfma_f32_32x32x16_bf16 v[48:63], v[100:103], v[80:83], v[48:63]
	v_mfma_f32_32x32x16_bf16 v[32:47], v[104:107], v[80:83], v[32:47]
	v_mfma_f32_32x32x16_bf16 v[16:31], v[88:91], v[80:83], v[16:31]
	s_andn2_b64 s[6:7], exec, s[16:17]
	v_mfma_f32_32x32x16_bf16 v[112:127], v[228:231], v[188:191], v[112:127]
	s_cbranch_vccnz .LBB0_608
	s_waitcnt vmcnt(0)
	ds_write_b128 v215, v[192:195] offset:9216
	s_and_b64 vcc, exec, s[4:5]
	s_cbranch_vccz .LBB0_609

; __device__ __forceinline__ float fexp2(float x) { return __builtin_amdgcn_exp2f(x); }
; #define MFMA(a, b, c) __builtin_amdgcn_mfma_f32_32x32x16_bf16((a), (b), (c), 0, 0, 0)
; #define LOADKV(t) do { \
;     _Pragma("unroll") for (int j = 0; j < NKC; ++j) if (j + 1 < NKC || k1) rk[j] = *(const u32x4*)(kh + (size_t)(t) * 64 * DQK + (size_t)(tid + 512 * j) * 8); \
;     _Pragma("unroll") for (int j = 0; j < NVC; ++j) rv[j] = *(const u32x4*)(vg0 + (size_t)(64 * j) * S + (size_t)(t) * 64); } while (0)
; #define STOREKV(slot) do { \
;     _Pragma("unroll") for (int j = 0; j < NKC; ++j) if (j + 1 < NKC || k1) *(u32x4*)(sK + (slot) * KSB + klo[j]) = rk[j]; \
;     _Pragma("unroll") for (int j = 0; j < NVC; ++j) *(u32x4*)(sV + (slot) * VSB + vlo[j]) = rv[j]; } while (0)
; template <int DQK, int DV>
; __device__ __forceinline__ void attn_pass2(const bf16_t* __restrict__ qh, const bf16_t* __restrict__ kh, const bf16_t* __restrict__ vth, int q0, char* smem, f32x16 (&o)[2][DV / 32], float kmax, int wvp) {
;     ...
;   for (int kt = 0; kt < NT; ++kt) {
;     const int cur = kt & 1;
;     __syncthreads();
;     if (kt + 1 < NT) { STOREKV(cur ^ 1); if (kt + 2 < NT) LOADKV(kt + 2); }
;     f32x16 s[2][2];
;     const char* kb0 = sK + cur * KSB + kofs;
; #pragma unroll
;     for (int ks = 0; ks < NKS; ++ks) {
;       const bf16x8 a0 = *(const bf16x8*)(kb0 + ks * 32), a1 = *(const bf16x8*)(kb0 + 32 * KP + ks * 32);
; #pragma unroll
;       for (int qb = 0; qb < 2; ++qb) {
;         if (ks == 0) {
;           f32x16 z;
; #pragma unroll
;           for (int i = 0; i < 16; ++i) z[i] = 0.f;
;           s[qb][0] = MFMA(a0, qf[qb][0], z); s[qb][1] = MFMA(a1, qf[qb][0], z);
;         } else { s[qb][0] = MFMA(a0, qf[qb][ks], s[qb][0]); s[qb][1] = MFMA(a1, qf[qb][ks], s[qb][1]); }
;       }
;     }
;     __builtin_amdgcn_sched_barrier(0);
; #pragma unroll
;     for (int qb = 0; qb < 2; ++qb) {
;       float rs0 = 0.f, rs1 = 0.f;
; #pragma unroll
;       for (int i = 0; i < 16; ++i) { s[qb][0][i] = fexp2(s[qb][0][i] - mref[qb]); s[qb][1][i] = fexp2(s[qb][1][i] - mref[qb]); rs0 += s[qb][0][i]; rs1 += s[qb][1][i]; }
;       l_run[qb] += rs0 + rs1;
;     }
.LBB0_1429:
	s_mulk_i32 s7, 0x2400
	v_add_u32_e32 v180, s7, v169
	ds_read_b128 v[64:67], v180
	ds_read_b128 v[176:179], v180 offset:32
	ds_read_b128 v[68:71], v180 offset:4608
	ds_read_b128 v[192:195], v180 offset:4640
	s_add_i32 s6, s6, 1
	s_waitcnt lgkmcnt(3)
	v_mfma_f32_32x32x16_bf16 v[112:127], v[64:67], v[128:131], v[236:251]
	s_waitcnt lgkmcnt(1)
	v_mfma_f32_32x32x16_bf16 v[96:111], v[68:71], v[128:131], v[236:251]
	v_mfma_f32_32x32x16_bf16 v[80:95], v[64:67], v[144:147], v[236:251]
	v_mfma_f32_32x32x16_bf16 v[64:79], v[68:71], v[144:147], v[236:251]
	v_mfma_f32_32x32x16_bf16 v[112:127], v[176:179], v[132:135], v[112:127]
	s_waitcnt lgkmcnt(0)
	v_mfma_f32_32x32x16_bf16 v[96:111], v[192:195], v[132:135], v[96:111]
	v_mfma_f32_32x32x16_bf16 v[80:95], v[176:179], v[148:151], v[80:95]
	v_mfma_f32_32x32x16_bf16 v[64:79], v[192:195], v[148:151], v[64:79]
	ds_read_b128 v[176:179], v180 offset:64
	ds_read_b128 v[192:195], v180 offset:96
	ds_read_b128 v[196:199], v180 offset:4672
	ds_read_b128 v[200:203], v180 offset:4704
	s_waitcnt lgkmcnt(3)
	v_mfma_f32_32x32x16_bf16 v[112:127], v[176:179], v[136:139], v[112:127]
	s_waitcnt lgkmcnt(1)
	v_mfma_f32_32x32x16_bf16 v[96:111], v[196:199], v[136:139], v[96:111]
	v_mfma_f32_32x32x16_bf16 v[80:95], v[176:179], v[152:155], v[80:95]
	v_mfma_f32_32x32x16_bf16 v[64:79], v[196:199], v[152:155], v[64:79]
	v_mfma_f32_32x32x16_bf16 v[112:127], v[192:195], v[140:143], v[112:127]
	s_waitcnt lgkmcnt(0)
	v_mfma_f32_32x32x16_bf16 v[96:111], v[200:203], v[140:143], v[96:111]
	v_mfma_f32_32x32x16_bf16 v[80:95], v[192:195], v[156:159], v[80:95]
	v_mfma_f32_32x32x16_bf16 v[64:79], v[200:203], v[156:159], v[64:79]
	v_add_u32_e32 v209, s7, v185
	v_lshl_add_u64 v[170:171], v[170:171], 0, s[52:53]
	v_lshl_add_u64 v[172:173], v[172:173], 0, s[54:55]
	s_nop 6
	v_exp_f32_e32 v186, v96
	v_exp_f32_e32 v97, v97
	v_exp_f32_e32 v177, v112
	v_exp_f32_e32 v113, v113
	v_exp_f32_e32 v179, v114
	v_exp_f32_e32 v187, v98
	v_add_f32_e32 v98, v97, v186
	v_exp_f32_e32 v115, v115
	v_exp_f32_e32 v190, v99
	v_exp_f32_e32 v204, v100
	v_exp_f32_e32 v99, v116
	v_exp_f32_e32 v117, v117
	v_add_f32_e32 v96, v113, v177
	v_exp_f32_e32 v101, v101
	v_add_f32_e32 v96, v179, v96
	v_exp_f32_e32 v181, v118
	v_add_f32_e32 v96, v115, v96
	v_add_f32_e32 v96, v99, v96
	v_add_f32_e32 v96, v117, v96
	v_add_f32_e32 v112, v181, v96
	v_exp_f32_e32 v176, v119
	v_exp_f32_e32 v178, v103
	v_add_f32_e32 v98, v187, v98
	v_exp_f32_e32 v205, v102
	v_exp_f32_e32 v180, v120
	v_exp_f32_e32 v96, v104
	v_exp_f32_e32 v104, v123
	v_add_f32_e32 v98, v190, v98
	v_exp_f32_e32 v100, v106
	v_exp_f32_e32 v106, v107
	v_add_f32_e32 v98, v204, v98
	v_exp_f32_e32 v118, v124
	v_add_f32_e32 v98, v101, v98
	v_exp_f32_e32 v120, v108
	v_add_f32_e32 v102, v205, v98
	v_exp_f32_e32 v124, v125
	v_exp_f32_e32 v116, v121
	v_exp_f32_e32 v108, v109
	v_exp_f32_e32 v114, v105
	v_exp_f32_e32 v98, v122
	v_exp_f32_e32 v122, v126
	v_exp_f32_e32 v110, v110
	v_exp_f32_e32 v126, v127
	v_exp_f32_e32 v103, v80
	v_exp_f32_e32 v107, v64
	v_exp_f32_e32 v109, v81
	v_exp_f32_e32 v65, v65
	v_exp_f32_e32 v121, v66
	v_add_f32_e32 v66, v109, v103
	v_add_f32_e32 v80, v65, v107
	v_add_f32_e32 v206, v121, v80
	v_exp_f32_e32 v207, v83
	v_exp_f32_e32 v64, v111
	v_exp_f32_e32 v111, v82
	v_exp_f32_e32 v208, v84
	ds_read_b128 v[80:83], v209 offset:18432
	ds_read_b128 v[196:199], v209 offset:18464
	ds_read_b128 v[200:203], v209 offset:23040
	v_exp_f32_e32 v212, v85
	v_exp_f32_e32 v213, v86
	v_cvt_pk_bf16_f32 v192, v177, v113
	v_exp_f32_e32 v177, v87
	v_cvt_pk_bf16_f32 v84, v103, v109
	v_exp_f32_e32 v109, v67
	v_add_f32_e32 v66, v111, v66
	v_cvt_pk_bf16_f32 v85, v111, v207
	v_exp_f32_e32 v111, v68
	v_cvt_pk_bf16_f32 v195, v181, v176
	v_exp_f32_e32 v181, v88
	v_cvt_pk_bf16_f32 v194, v99, v117
	v_exp_f32_e32 v117, v89
	v_cvt_pk_bf16_f32 v193, v179, v115
	v_cvt_pk_bf16_f32 v86, v208, v212
	v_cvt_pk_bf16_f32 v87, v213, v177
	v_exp_f32_e32 v99, v90
	s_waitcnt lgkmcnt(2)
; __device__ __forceinline__ unsigned pk2(float lo, float hi) { f32x2_t v = {lo, hi}; bf16x2_t b = __builtin_convertvector(v, bf16x2_t); return __builtin_bit_cast(unsigned, b); }
; __device__ __forceinline__ float fexp2(float x) { return __builtin_amdgcn_exp2f(x); }
; #define MFMA(a, b, c) __builtin_amdgcn_mfma_f32_32x32x16_bf16((a), (b), (c), 0, 0, 0)
; template <int DQK, int DV>
; __device__ __forceinline__ void attn_pass2(const bf16_t* __restrict__ qh, const bf16_t* __restrict__ kh, const bf16_t* __restrict__ vth, int q0, char* smem, f32x16 (&o)[2][DV / 32], float kmax, int wvp) {
;     ...
;       for (int i = 0; i < 16; ++i) { s[qb][0][i] = fexp2(s[qb][0][i] - mref[qb]); s[qb][1][i] = fexp2(s[qb][1][i] - mref[qb]); rs0 += s[qb][0][i]; rs1 += s[qb][1][i]; }
;       l_run[qb] += rs0 + rs1;
;     }
;     const char* vb0 = sV + cur * VSB + vofs;
; #pragma unroll
;     for (int kb = 0; kb < 2; ++kb)
; #pragma unroll
;       for (int s2 = 0; s2 < 2; ++s2) {
;         bf16x8 pq[2];
; #pragma unroll
;         for (int qb = 0; qb < 2; ++qb) {
;           u32x4 w;
;           w.x = pk2(s[qb][kb][8 * s2 + 0], s[qb][kb][8 * s2 + 1]); w.y = pk2(s[qb][kb][8 * s2 + 2], s[qb][kb][8 * s2 + 3]);
;           w.z = pk2(s[qb][kb][8 * s2 + 4], s[qb][kb][8 * s2 + 5]); w.w = pk2(s[qb][kb][8 * s2 + 6], s[qb][kb][8 * s2 + 7]);
;           pq[qb] = __builtin_bit_cast(bf16x8, w);
;         }
; #pragma unroll
;         for (int eb = 0; eb < NEB; ++eb) {
;           const bf16x8 a = *(const bf16x8*)(vb0 + eb * 32 * VP + (32 * kb + 16 * s2) * 2);
; #pragma unroll
;           for (int qb = 0; qb < 2; ++qb) o[qb][eb] = MFMA(a, pq[qb], o[qb][eb]);
;         }
;       }
	v_mfma_f32_32x32x16_bf16 v[48:63], v[80:83], v[192:195], v[48:63]
	v_exp_f32_e32 v105, v91
	v_exp_f32_e32 v119, v92
	v_exp_f32_e32 v125, v93
	v_mfma_f32_32x32x16_bf16 v[16:31], v[80:83], v[84:87], v[16:31]
	ds_read_b128 v[80:83], v209 offset:23072
	v_exp_f32_e32 v123, v94
	v_exp_f32_e32 v92, v69
	v_exp_f32_e32 v127, v95
	s_waitcnt lgkmcnt(1)
	v_mfma_f32_32x32x16_bf16 v[0:15], v[200:203], v[84:87], v[0:15]
	v_exp_f32_e32 v93, v70
	v_add_f32_e32 v66, v207, v66
	v_add_f32_e32 v67, v109, v206
	v_add_f32_e32 v66, v208, v66
	v_add_f32_e32 v67, v111, v67
	v_add_f32_e32 v66, v212, v66
	v_add_f32_e32 v67, v92, v67
	v_mfma_f32_32x32x16_bf16 v[32:47], v[200:203], v[192:195], v[32:47]
	v_cvt_pk_bf16_f32 v84, v180, v116
	v_cvt_pk_bf16_f32 v85, v98, v104
	v_cvt_pk_bf16_f32 v86, v118, v124
	v_cvt_pk_bf16_f32 v87, v122, v126
	v_cvt_pk_bf16_f32 v88, v181, v117
	v_cvt_pk_bf16_f32 v89, v99, v105
	v_cvt_pk_bf16_f32 v90, v119, v125
	v_cvt_pk_bf16_f32 v91, v123, v127
	v_add_f32_e32 v113, v213, v66
	v_add_f32_e32 v103, v93, v67
	ds_read_b128 v[66:69], v209 offset:18496
	v_mfma_f32_32x32x16_bf16 v[48:63], v[196:199], v[84:87], v[48:63]
	v_exp_f32_e32 v179, v71
	v_mov_b32_e32 v70, v72
	v_exp_f32_e32 v115, v73
	v_cvt_pk_bf16_f32 v71, v121, v109
	v_cvt_pk_bf16_f32 v72, v111, v92
	v_cvt_pk_bf16_f32 v73, v93, v179
	v_mfma_f32_32x32x16_bf16 v[16:31], v[196:199], v[88:91], v[16:31]
	s_cmpk_lg_i32 s6, 0x80
	s_waitcnt lgkmcnt(1)
	v_mfma_f32_32x32x16_bf16 v[0:15], v[80:83], v[88:91], v[0:15]
	ds_read_b128 v[88:91], v209 offset:23104
	v_mfma_f32_32x32x16_bf16 v[32:47], v[80:83], v[84:87], v[32:47]
	v_cvt_pk_bf16_f32 v80, v186, v97
	v_exp_f32_e32 v97, v70
	v_cvt_pk_bf16_f32 v70, v107, v65
	v_cvt_pk_bf16_f32 v81, v187, v190
	v_cvt_pk_bf16_f32 v82, v204, v101
	v_cvt_pk_bf16_f32 v83, v205, v178
	v_exp_f32_e32 v101, v74
	ds_read_b128 v[84:87], v209 offset:18528
	s_waitcnt lgkmcnt(2)
	v_mfma_f32_32x32x16_bf16 v[48:63], v[66:69], v[80:83], v[48:63]
	v_exp_f32_e32 v107, v75
	v_exp_f32_e32 v121, v76
	v_exp_f32_e32 v109, v77
	v_exp_f32_e32 v111, v78
	v_mfma_f32_32x32x16_bf16 v[16:31], v[66:69], v[70:73], v[16:31]
	ds_read_b128 v[66:69], v209 offset:23136
	v_exp_f32_e32 v65, v79
	v_add_f32_e32 v74, v178, v102
	v_add_f32_e32 v75, v179, v103
	s_nop 0
	v_add_f32_e32 v74, v96, v74
	v_add_f32_e32 v75, v97, v75
	s_waitcnt lgkmcnt(2)
	v_mfma_f32_32x32x16_bf16 v[32:47], v[88:91], v[80:83], v[32:47]
	v_add_f32_e64 v80, v114, v74
	v_add_f32_e64 v81, v115, v75
	v_cvt_pk_bf16_f32 v74, v97, v115
	v_cvt_pk_bf16_f32 v75, v101, v107
	v_add_f32_e64 v80, v100, v80
	v_add_f32_e64 v81, v101, v81
	v_add_f32_e32 v80, v106, v80
	v_add_f32_e32 v81, v107, v81
	v_mfma_f32_32x32x16_bf16 v[0:15], v[88:91], v[70:73], v[0:15]
	v_add_f32_e64 v70, v176, v112
	v_add_f32_e64 v71, v177, v113
	v_cvt_pk_bf16_f32 v72, v120, v108
	v_add_f32_e64 v76, v180, v70
	v_add_f32_e64 v77, v181, v71
	v_cvt_pk_bf16_f32 v70, v96, v114
	v_cvt_pk_bf16_f32 v71, v100, v106
	v_cvt_pk_bf16_f32 v73, v110, v64
	v_add_f32_e32 v78, v116, v76
	v_add_f32_e32 v79, v117, v77
	v_cvt_pk_bf16_f32 v76, v121, v109
	v_cvt_pk_bf16_f32 v77, v111, v65
	s_waitcnt lgkmcnt(1)
	v_mfma_f32_32x32x16_bf16 v[48:63], v[84:87], v[70:73], v[48:63]
	v_add_f32_e64 v78, v98, v78
	v_add_f32_e64 v79, v99, v79
	v_add_f32_e64 v80, v120, v80
	v_add_f32_e64 v81, v121, v81
	v_add_f32_e64 v78, v104, v78
	v_add_f32_e64 v79, v105, v79
	v_add_f32_e32 v78, v118, v78
	v_add_f32_e32 v79, v119, v79
	s_nop 0
	v_add_f32_e32 v78, v124, v78
	v_add_f32_e32 v79, v125, v79
	v_mfma_f32_32x32x16_bf16 v[16:31], v[84:87], v[74:77], v[16:31]
	s_waitcnt lgkmcnt(0)
	v_mfma_f32_32x32x16_bf16 v[32:47], v[66:69], v[70:73], v[32:47]
	v_add_f32_e64 v70, v108, v80
	v_add_f32_e64 v71, v109, v81
	v_add_f32_e64 v72, v122, v78
	v_add_f32_e64 v73, v123, v79
	v_add_f32_e64 v70, v110, v70
	v_add_f32_e64 v71, v111, v71
	v_add_f32_e32 v72, v126, v72
	v_add_f32_e32 v73, v127, v73
	v_add_f32_e32 v64, v64, v70
	v_add_f32_e32 v65, v65, v71
	s_nop 0
	v_add_f32_e32 v64, v72, v64
	v_add_f32_e32 v65, v73, v65
	v_mfma_f32_32x32x16_bf16 v[0:15], v[66:69], v[74:77], v[0:15]
	v_add_f32_e64 v174, v174, v64
	v_add_f32_e64 v175, v175, v65
	s_cbranch_scc0 .LBB0_1433

; __device__ __forceinline__ float fexp2(float x) { return __builtin_amdgcn_exp2f(x); }
; #define MFMA(a, b, c) __builtin_amdgcn_mfma_f32_32x32x16_bf16((a), (b), (c), 0, 0, 0)
; #define LOADKV(t) do { \
;     _Pragma("unroll") for (int j = 0; j < NKC; ++j) if (j + 1 < NKC || k1) rk[j] = *(const u32x4*)(kh + (size_t)(t) * 64 * DQK + (size_t)(tid + 512 * j) * 8); \
;     _Pragma("unroll") for (int j = 0; j < NVC; ++j) rv[j] = *(const u32x4*)(vg0 + (size_t)(64 * j) * S + (size_t)(t) * 64); } while (0)
; #define STOREKV(slot) do { \
;     _Pragma("unroll") for (int j = 0; j < NKC; ++j) if (j + 1 < NKC || k1) *(u32x4*)(sK + (slot) * KSB + klo[j]) = rk[j]; \
;     _Pragma("unroll") for (int j = 0; j < NVC; ++j) *(u32x4*)(sV + (slot) * VSB + vlo[j]) = rv[j]; } while (0)
; template <int DQK, int DV>
; __device__ __forceinline__ void attn_pass2(const bf16_t* __restrict__ qh, const bf16_t* __restrict__ kh, const bf16_t* __restrict__ vth, int q0, char* smem, f32x16 (&o)[2][DV / 32], float kmax, int wvp) {
;     ...
;   for (int kt = 0; kt < NT; ++kt) {
;     const int cur = kt & 1;
;     __syncthreads();
;     if (kt + 1 < NT) { STOREKV(cur ^ 1); if (kt + 2 < NT) LOADKV(kt + 2); }
;     f32x16 s[2][2];
;     const char* kb0 = sK + cur * KSB + kofs;
; #pragma unroll
;     for (int ks = 0; ks < NKS; ++ks) {
;       const bf16x8 a0 = *(const bf16x8*)(kb0 + ks * 32), a1 = *(const bf16x8*)(kb0 + 32 * KP + ks * 32);
; #pragma unroll
;       for (int qb = 0; qb < 2; ++qb) {
;         if (ks == 0) {
;           f32x16 z;
; #pragma unroll
;           for (int i = 0; i < 16; ++i) z[i] = 0.f;
;           s[qb][0] = MFMA(a0, qf[qb][0], z); s[qb][1] = MFMA(a1, qf[qb][0], z);
;         } else { s[qb][0] = MFMA(a0, qf[qb][ks], s[qb][0]); s[qb][1] = MFMA(a1, qf[qb][ks], s[qb][1]); }
;       }
;     }
;     __builtin_amdgcn_sched_barrier(0);
; #pragma unroll
;     for (int qb = 0; qb < 2; ++qb) {
;       float rs0 = 0.f, rs1 = 0.f;
; #pragma unroll
;       for (int i = 0; i < 16; ++i) { s[qb][0][i] = fexp2(s[qb][0][i] - mref[qb]); s[qb][1][i] = fexp2(s[qb][1][i] - mref[qb]); rs0 += s[qb][0][i]; rs1 += s[qb][1][i]; }
;       l_run[qb] += rs0 + rs1;
;     }
.LBB0_1445:
	s_mul_i32 s8, s11, 0x3400
	v_add_u32_e32 v190, s8, v215
	ds_read_b128 v[64:67], v190
	ds_read_b128 v[202:205], v190 offset:32
	ds_read_b128 v[68:71], v190 offset:6656
	ds_read_b128 v[206:209], v190 offset:6688
	s_waitcnt lgkmcnt(3)
	v_mfma_f32_32x32x16_bf16 v[112:127], v[64:67], v[128:131], v[236:251]
	s_waitcnt lgkmcnt(1)
	v_mfma_f32_32x32x16_bf16 v[96:111], v[68:71], v[128:131], v[236:251]
	v_mfma_f32_32x32x16_bf16 v[80:95], v[64:67], v[152:155], v[236:251]
	v_mfma_f32_32x32x16_bf16 v[64:79], v[68:71], v[152:155], v[236:251]
	v_mfma_f32_32x32x16_bf16 v[112:127], v[202:205], v[132:135], v[112:127]
	s_waitcnt lgkmcnt(0)
	v_mfma_f32_32x32x16_bf16 v[96:111], v[206:209], v[132:135], v[96:111]
	v_mfma_f32_32x32x16_bf16 v[80:95], v[202:205], v[156:159], v[80:95]
	v_mfma_f32_32x32x16_bf16 v[64:79], v[206:209], v[156:159], v[64:79]
	ds_read_b128 v[202:205], v190 offset:64
	ds_read_b128 v[206:209], v190 offset:96
	ds_read_b128 v[218:221], v190 offset:6720
	ds_read_b128 v[222:225], v190 offset:6752
	s_waitcnt lgkmcnt(3)
	v_mfma_f32_32x32x16_bf16 v[112:127], v[202:205], v[136:139], v[112:127]
	s_waitcnt lgkmcnt(1)
	v_mfma_f32_32x32x16_bf16 v[96:111], v[218:221], v[136:139], v[96:111]
	v_mfma_f32_32x32x16_bf16 v[80:95], v[202:205], v[160:163], v[80:95]
	v_mfma_f32_32x32x16_bf16 v[64:79], v[218:221], v[160:163], v[64:79]
	v_mfma_f32_32x32x16_bf16 v[112:127], v[206:209], v[140:143], v[112:127]
	s_waitcnt lgkmcnt(0)
	v_mfma_f32_32x32x16_bf16 v[96:111], v[222:225], v[140:143], v[96:111]
	v_mfma_f32_32x32x16_bf16 v[80:95], v[206:209], v[164:167], v[80:95]
	ds_read_b128 v[202:205], v190 offset:128
	ds_read_b128 v[206:209], v190 offset:160
	v_mfma_f32_32x32x16_bf16 v[64:79], v[222:225], v[164:167], v[64:79]
	ds_read_b128 v[218:221], v190 offset:6784
	ds_read_b128 v[222:225], v190 offset:6816
	s_waitcnt lgkmcnt(3)
	v_mfma_f32_32x32x16_bf16 v[112:127], v[202:205], v[144:147], v[112:127]
	s_waitcnt lgkmcnt(1)
	v_mfma_f32_32x32x16_bf16 v[96:111], v[218:221], v[144:147], v[96:111]
	v_mfma_f32_32x32x16_bf16 v[80:95], v[202:205], v[168:171], v[80:95]
	v_mfma_f32_32x32x16_bf16 v[64:79], v[218:221], v[168:171], v[64:79]
	v_mfma_f32_32x32x16_bf16 v[112:127], v[206:209], v[148:151], v[112:127]
	s_waitcnt lgkmcnt(0)
	v_mfma_f32_32x32x16_bf16 v[96:111], v[222:225], v[148:151], v[96:111]
	v_mfma_f32_32x32x16_bf16 v[80:95], v[206:209], v[172:175], v[80:95]
	v_mfma_f32_32x32x16_bf16 v[64:79], v[222:225], v[172:175], v[64:79]
	s_mulk_i32 s11, 0x2400
	v_lshl_add_u64 v[194:195], v[194:195], 0, s[54:55]
	v_add_u32_e32 v233, s11, v216
	s_nop 6
	v_exp_f32_e32 v96, v96
	v_exp_f32_e32 v112, v112
	v_exp_f32_e32 v208, v97
	v_exp_f32_e32 v204, v113
	v_exp_f32_e32 v227, v99
	v_exp_f32_e32 v114, v114
	v_exp_f32_e32 v116, v116
	v_exp_f32_e32 v217, v98
	v_exp_f32_e32 v100, v100
	v_add_f32_e32 v98, v208, v96
	v_exp_f32_e32 v202, v117
	v_add_f32_e32 v97, v204, v112
	v_exp_f32_e32 v190, v115
	v_exp_f32_e32 v228, v101
	v_exp_f32_e32 v118, v118
	v_add_f32_e32 v98, v217, v98
	v_exp_f32_e32 v229, v102
	v_add_f32_e32 v97, v114, v97
	v_add_f32_e32 v98, v227, v98
	v_add_f32_e32 v97, v190, v97
	v_add_f32_e32 v98, v100, v98
	v_add_f32_e32 v97, v116, v97
	v_add_f32_e32 v98, v228, v98
	v_add_f32_e32 v97, v202, v97
	v_add_f32_e32 v113, v229, v98
	v_add_f32_e32 v115, v118, v97
	v_exp_f32_e32 v203, v119
	v_exp_f32_e32 v119, v121
	v_exp_f32_e32 v117, v105
	v_exp_f32_e32 v99, v122
	v_exp_f32_e32 v101, v106
	v_exp_f32_e32 v205, v103
	v_exp_f32_e32 v103, v123
	v_exp_f32_e32 v105, v107
	v_exp_f32_e32 v107, v124
	v_exp_f32_e32 v121, v108
	v_exp_f32_e32 v125, v125
	v_exp_f32_e32 v109, v109
	v_exp_f32_e32 v123, v126
	v_exp_f32_e32 v209, v110
	v_exp_f32_e32 v127, v127
	v_exp_f32_e32 v98, v80
	v_exp_f32_e32 v102, v81
	v_exp_f32_e32 v108, v65
	v_exp_f32_e32 v207, v120
	v_exp_f32_e32 v97, v104
	v_exp_f32_e32 v104, v64
	v_exp_f32_e32 v106, v82
	v_exp_f32_e32 v111, v111
	v_exp_f32_e32 v110, v66
	v_add_f32_e32 v64, v102, v98
	v_add_f32_e32 v120, v106, v64
	v_add_f32_e32 v65, v108, v104
	v_exp_f32_e32 v231, v83
	v_add_f32_e32 v230, v110, v65
	v_mov_b32_e32 v122, v67
	v_exp_f32_e32 v232, v84
	ds_read_b128 v[64:67], v233 offset:26624
	ds_read_b128 v[218:221], v233 offset:26656
	v_exp_f32_e32 v234, v85
	ds_read_b128 v[222:225], v233 offset:31232
	v_exp_f32_e32 v235, v86
	v_cvt_pk_bf16_f32 v82, v116, v202
	v_exp_f32_e32 v202, v87
	v_cvt_pk_bf16_f32 v80, v112, v204
	v_cvt_pk_bf16_f32 v81, v114, v190
	v_cvt_pk_bf16_f32 v83, v118, v203
	v_cvt_pk_bf16_f32 v84, v98, v102
	v_cvt_pk_bf16_f32 v85, v106, v231
	v_cvt_pk_bf16_f32 v86, v232, v234
	v_cvt_pk_bf16_f32 v87, v235, v202
	s_waitcnt lgkmcnt(2)
; __device__ __forceinline__ unsigned pk2(float lo, float hi) { f32x2_t v = {lo, hi}; bf16x2_t b = __builtin_convertvector(v, bf16x2_t); return __builtin_bit_cast(unsigned, b); }
; __device__ __forceinline__ float fexp2(float x) { return __builtin_amdgcn_exp2f(x); }
; #define MFMA(a, b, c) __builtin_amdgcn_mfma_f32_32x32x16_bf16((a), (b), (c), 0, 0, 0)
; template <int DQK, int DV>
; __device__ __forceinline__ void attn_pass2(const bf16_t* __restrict__ qh, const bf16_t* __restrict__ kh, const bf16_t* __restrict__ vth, int q0, char* smem, f32x16 (&o)[2][DV / 32], float kmax, int wvp) {
;     ...
;       for (int i = 0; i < 16; ++i) { s[qb][0][i] = fexp2(s[qb][0][i] - mref[qb]); s[qb][1][i] = fexp2(s[qb][1][i] - mref[qb]); rs0 += s[qb][0][i]; rs1 += s[qb][1][i]; }
;       l_run[qb] += rs0 + rs1;
;     }
;     const char* vb0 = sV + cur * VSB + vofs;
; #pragma unroll
;     for (int kb = 0; kb < 2; ++kb)
; #pragma unroll
;       for (int s2 = 0; s2 < 2; ++s2) {
;         bf16x8 pq[2];
; #pragma unroll
;         for (int qb = 0; qb < 2; ++qb) {
;           u32x4 w;
;           w.x = pk2(s[qb][kb][8 * s2 + 0], s[qb][kb][8 * s2 + 1]); w.y = pk2(s[qb][kb][8 * s2 + 2], s[qb][kb][8 * s2 + 3]);
;           w.z = pk2(s[qb][kb][8 * s2 + 4], s[qb][kb][8 * s2 + 5]); w.w = pk2(s[qb][kb][8 * s2 + 6], s[qb][kb][8 * s2 + 7]);
;           pq[qb] = __builtin_bit_cast(bf16x8, w);
;         }
; #pragma unroll
;         for (int eb = 0; eb < NEB; ++eb) {
;           const bf16x8 a = *(const bf16x8*)(vb0 + eb * 32 * VP + (32 * kb + 16 * s2) * 2);
; #pragma unroll
;           for (int qb = 0; qb < 2; ++qb) o[qb][eb] = MFMA(a, pq[qb], o[qb][eb]);
;         }
;       }
	v_mfma_f32_32x32x16_bf16 v[48:63], v[64:67], v[80:83], v[48:63]
	v_exp_f32_e32 v116, v122
	s_add_u32 s6, s6, 0x3000
	s_addc_u32 s7, s7, 0
	s_add_i32 s10, s10, 1
	v_mfma_f32_32x32x16_bf16 v[16:31], v[64:67], v[84:87], v[16:31]
	v_exp_f32_e32 v190, v68
	v_exp_f32_e32 v206, v88
	ds_read_b128 v[64:67], v233 offset:31264
	v_exp_f32_e32 v118, v89
	s_waitcnt lgkmcnt(1)
	v_mfma_f32_32x32x16_bf16 v[32:47], v[222:225], v[80:83], v[32:47]
	v_exp_f32_e32 v98, v90
	v_exp_f32_e32 v102, v91
	v_exp_f32_e32 v106, v92
	v_exp_f32_e32 v124, v93
	v_mfma_f32_32x32x16_bf16 v[0:15], v[222:225], v[84:87], v[0:15]
	v_exp_f32_e32 v122, v94
	v_exp_f32_e32 v89, v69
	v_exp_f32_e32 v126, v95
	v_exp_f32_e32 v90, v70
	v_cvt_pk_bf16_f32 v80, v207, v119
	v_cvt_pk_bf16_f32 v81, v99, v103
	v_cvt_pk_bf16_f32 v82, v107, v125
	v_cvt_pk_bf16_f32 v83, v123, v127
	v_add_f32_e32 v68, v231, v120
	v_add_f32_e32 v88, v116, v230
	v_mfma_f32_32x32x16_bf16 v[48:63], v[218:221], v[80:83], v[48:63]
	v_add_f32_e32 v68, v232, v68
	v_add_f32_e32 v88, v190, v88
	v_add_f32_e32 v68, v234, v68
	v_add_f32_e32 v69, v89, v88
	v_cvt_pk_bf16_f32 v84, v206, v118
	v_cvt_pk_bf16_f32 v85, v98, v102
	v_cvt_pk_bf16_f32 v86, v106, v124
	s_waitcnt lgkmcnt(0)
	v_mfma_f32_32x32x16_bf16 v[32:47], v[64:67], v[80:83], v[32:47]
	v_exp_f32_e32 v204, v71
	v_cvt_pk_bf16_f32 v87, v122, v126
	v_add_f32_e32 v114, v235, v68
	v_add_f32_e32 v112, v90, v69
	ds_read_b128 v[68:71], v233 offset:26688
	ds_read_b128 v[80:83], v233 offset:26720
	v_mfma_f32_32x32x16_bf16 v[16:31], v[218:221], v[84:87], v[16:31]
	s_cmp_lg_u32 s6, 0x180000
	v_mfma_f32_32x32x16_bf16 v[0:15], v[64:67], v[84:87], v[0:15]
	v_cvt_pk_bf16_f32 v86, v190, v89
	v_cvt_pk_bf16_f32 v87, v90, v204
	ds_read_b128 v[88:91], v233 offset:31296
	v_cvt_pk_bf16_f32 v64, v96, v208
	v_cvt_pk_bf16_f32 v65, v217, v227
	v_cvt_pk_bf16_f32 v66, v100, v228
	v_cvt_pk_bf16_f32 v67, v229, v205
	v_cvt_pk_bf16_f32 v84, v104, v108
	v_cvt_pk_bf16_f32 v85, v110, v116
	s_waitcnt lgkmcnt(2)
	v_mfma_f32_32x32x16_bf16 v[48:63], v[68:71], v[64:67], v[48:63]
	v_exp_f32_e32 v96, v72
	v_exp_f32_e32 v116, v73
	v_exp_f32_e32 v120, v76
	v_add_f32_e32 v72, v204, v112
	v_add_f32_e32 v73, v205, v113
	v_mfma_f32_32x32x16_bf16 v[16:31], v[68:71], v[84:87], v[16:31]
	v_exp_f32_e32 v100, v74
	v_exp_f32_e32 v104, v75
	ds_read_b128 v[68:71], v233 offset:31328
	v_add_f32_e32 v72, v96, v72
	v_add_f32_e32 v73, v97, v73
	s_waitcnt lgkmcnt(1)
	v_mfma_f32_32x32x16_bf16 v[32:47], v[88:91], v[64:67], v[32:47]
	v_exp_f32_e32 v108, v77
	v_exp_f32_e32 v208, v78
	v_exp_f32_e32 v110, v79
	v_add_f32_e32 v64, v202, v114
	v_add_f32_e32 v65, v203, v115
	v_mfma_f32_32x32x16_bf16 v[0:15], v[88:91], v[84:87], v[0:15]
	v_add_f32_e64 v74, v206, v64
	v_add_f32_e64 v75, v207, v65
	v_cvt_pk_bf16_f32 v64, v97, v117
	v_cvt_pk_bf16_f32 v65, v101, v105
	v_cvt_pk_bf16_f32 v66, v121, v109
	v_cvt_pk_bf16_f32 v67, v209, v111
	v_add_f32_e32 v76, v118, v74
	v_add_f32_e32 v77, v119, v75
	v_add_f32_e32 v78, v116, v72
	v_add_f32_e32 v79, v117, v73
	v_cvt_pk_bf16_f32 v72, v96, v116
	v_cvt_pk_bf16_f32 v73, v100, v104
	v_cvt_pk_bf16_f32 v74, v120, v108
	v_cvt_pk_bf16_f32 v75, v208, v110
	v_mfma_f32_32x32x16_bf16 v[48:63], v[80:83], v[64:67], v[48:63]
	v_add_f32_e64 v76, v98, v76
	v_add_f32_e64 v77, v99, v77
	v_add_f32_e64 v78, v100, v78
	v_add_f32_e64 v79, v101, v79
	v_add_f32_e64 v76, v102, v76
	v_add_f32_e64 v77, v103, v77
	v_add_f32_e32 v78, v104, v78
	v_add_f32_e32 v79, v105, v79
	v_add_f32_e32 v76, v106, v76
	v_add_f32_e32 v77, v107, v77
	v_add_f32_e32 v78, v120, v78
	v_add_f32_e32 v79, v121, v79
	v_add_f32_e32 v76, v124, v76
	v_add_f32_e32 v77, v125, v77
	v_mfma_f32_32x32x16_bf16 v[16:31], v[80:83], v[72:75], v[16:31]
	s_waitcnt lgkmcnt(0)
	v_mfma_f32_32x32x16_bf16 v[32:47], v[68:71], v[64:67], v[32:47]
	v_add_f32_e64 v64, v108, v78
	v_add_f32_e64 v65, v109, v79
	v_add_f32_e64 v66, v122, v76
	v_add_f32_e64 v67, v123, v77
	v_add_f32_e64 v64, v208, v64
	v_add_f32_e64 v65, v209, v65
	v_add_f32_e32 v66, v126, v66
	v_add_f32_e32 v67, v127, v67
	v_add_f32_e32 v64, v110, v64
	v_add_f32_e32 v65, v111, v65
	s_nop 0
	v_add_f32_e32 v64, v66, v64
	v_add_f32_e32 v65, v67, v65
	v_mfma_f32_32x32x16_bf16 v[0:15], v[68:71], v[72:75], v[0:15]
	v_add_f32_e64 v200, v200, v64
	v_add_f32_e64 v201, v201, v65
	s_cbranch_scc0 .LBB0_1425
